# PRO adaLN-modulation GEMV: w_ada loads software-pipelined three k-groups ahead (4 rotating register sets), same accumulation order
# speedup vs baseline: 1.0051x; 1.0046x over previous
;     __device__ __forceinline__ const float* in(int i) const { return (const float*)(const __attribute__((address_space(1))) float*)ld(i); }
; template <int PART>
; __device__ __forceinline__ void prologue(const KPD& kp, unsigned char* lds, int tid, int lane, int wave) {
;     ...
;         float a0 = 0.f, a1 = 0.f, a2 = 0.f, a3 = 0.f, a4 = 0.f;
;         const float* w = kp.in(I_WADA) + (size_t)l * D * 6144 + n0 + lane;
;         for (int k = wave * 128; k < wave * 128 + 128; ++k) { const float wv = w[(size_t)k * 6144];
;             a0 += cs[k] * wv; a1 += cs[1024 + k] * wv; a2 += cs[2048 + k] * wv; a3 += cs[3072 + k] * wv; a4 += cs[4096 + k] * wv; }
;         red[(wave * 5 + 0) * 64 + lane] = a0; red[(wave * 5 + 1) * 64 + lane] = a1; red[(wave * 5 + 2) * 64 + lane] = a2; red[(wave * 5 + 3) * 64 + lane] = a3; red[(wave * 5 + 4) * 64 + lane] = a4;
.LBB0_22:
	s_mov_b64 s[22:23], 0
	v_lshl_add_u64 v[82:83], v[14:15], 0, s[22:23]
	v_add_co_u32_e64 v84, s[0:1], s12, v82
	s_nop 1
	v_addc_co_u32_e64 v85, s[0:1], 0, v83, s[0:1]
	v_add_co_u32_e64 v86, s[0:1], s16, v82
	s_nop 1
	v_addc_co_u32_e64 v87, s[0:1], 0, v83, s[0:1]
	v_add_co_u32_e64 v88, s[0:1], s17, v82
	s_nop 1
	v_addc_co_u32_e64 v89, s[0:1], 0, v83, s[0:1]
	global_load_dword v46, v[82:83], off
	global_load_dword v48, v[84:85], off
	global_load_dword v50, v[86:87], off
	global_load_dword v52, v[88:89], off
	s_add_u32 s24, s22, 0x18000
	s_cmp_lt_u32 s24, 0x300000
	s_cselect_b32 s22, s24, s22
	v_lshl_add_u64 v[82:83], v[14:15], 0, s[22:23]
	v_add_co_u32_e64 v84, s[0:1], s12, v82
	s_nop 1
	v_addc_co_u32_e64 v85, s[0:1], 0, v83, s[0:1]
	v_add_co_u32_e64 v86, s[0:1], s16, v82
	s_nop 1
	v_addc_co_u32_e64 v87, s[0:1], 0, v83, s[0:1]
	v_add_co_u32_e64 v88, s[0:1], s17, v82
	s_nop 1
	v_addc_co_u32_e64 v89, s[0:1], 0, v83, s[0:1]
	global_load_dword v58, v[82:83], off
	global_load_dword v60, v[84:85], off
	global_load_dword v62, v[86:87], off
	global_load_dword v64, v[88:89], off
	s_add_u32 s24, s22, 0x18000
	s_cmp_lt_u32 s24, 0x300000
	s_cselect_b32 s22, s24, s22
	v_lshl_add_u64 v[82:83], v[14:15], 0, s[22:23]
	v_add_co_u32_e64 v84, s[0:1], s12, v82
	s_nop 1
	v_addc_co_u32_e64 v85, s[0:1], 0, v83, s[0:1]
	v_add_co_u32_e64 v86, s[0:1], s16, v82
	s_nop 1
	v_addc_co_u32_e64 v87, s[0:1], 0, v83, s[0:1]
	v_add_co_u32_e64 v88, s[0:1], s17, v82
	s_nop 1
	v_addc_co_u32_e64 v89, s[0:1], 0, v83, s[0:1]
	global_load_dword v66, v[82:83], off
	global_load_dword v68, v[84:85], off
	global_load_dword v70, v[86:87], off
	global_load_dword v72, v[88:89], off
	s_add_u32 s24, s22, 0x18000
	s_cmp_lt_u32 s24, 0x300000
	s_cselect_b32 s22, s24, s22
.Lpro_loop:
	v_lshl_add_u64 v[82:83], v[14:15], 0, s[22:23]
	v_add_co_u32_e64 v84, s[0:1], s12, v82
	s_nop 1
	v_addc_co_u32_e64 v85, s[0:1], 0, v83, s[0:1]
	v_add_co_u32_e64 v86, s[0:1], s16, v82
	s_nop 1
	v_addc_co_u32_e64 v87, s[0:1], 0, v83, s[0:1]
	v_add_co_u32_e64 v88, s[0:1], s17, v82
	s_nop 1
	v_addc_co_u32_e64 v89, s[0:1], 0, v83, s[0:1]
	global_load_dword v74, v[82:83], off
	global_load_dword v76, v[84:85], off
	global_load_dword v78, v[86:87], off
	global_load_dword v80, v[88:89], off
	s_add_u32 s24, s22, 0x18000
	s_cmp_lt_u32 s24, 0x300000
	s_cselect_b32 s22, s24, s22
	v_mov_b32_e32 v13, s20
	ds_read_b128 v[26:29], v13
	ds_read_b128 v[30:33], v13 offset:4096
	ds_read_b128 v[34:37], v13 offset:8192
	ds_read_b128 v[38:41], v13 offset:12288
	ds_read_b128 v[42:45], v13 offset:16384
	s_add_u32 s10, s10, 0x18000
	s_addc_u32 s11, s11, 0
	s_waitcnt lgkmcnt(3)
	v_mov_b32_e32 v55, v30
	s_waitcnt lgkmcnt(2)
	v_mov_b32_e32 v54, v34
	s_waitcnt lgkmcnt(1)
	v_mov_b32_e32 v57, v38
	s_waitcnt lgkmcnt(0)
	v_mov_b32_e32 v56, v42
	v_mov_b32_e32 v30, v35
	v_mov_b32_e32 v38, v43
	v_mov_b32_e32 v34, v36
	v_mov_b32_e32 v35, v32
	v_mov_b32_e32 v42, v44
	v_mov_b32_e32 v43, v40
	s_add_i32 s20, s20, 16
	v_mov_b32_e32 v32, v37
	v_mov_b32_e32 v40, v45
	s_waitcnt vmcnt(15)
	v_fmac_f32_e32 v4, v46, v26
	v_pk_fma_f32 v[18:19], v[46:47], v[54:55], v[18:19] op_sel_hi:[0,1,1]
	v_pk_fma_f32 v[16:17], v[46:47], v[56:57], v[16:17] op_sel_hi:[0,1,1]
	s_waitcnt vmcnt(14)
	v_fmac_f32_e32 v4, v48, v27
	v_pk_fma_f32 v[18:19], v[48:49], v[30:31], v[18:19] op_sel_hi:[0,1,1]
	v_pk_fma_f32 v[16:17], v[48:49], v[38:39], v[16:17] op_sel_hi:[0,1,1]
	s_waitcnt vmcnt(13)
	v_fmac_f32_e32 v4, v50, v28
	v_pk_fma_f32 v[18:19], v[50:51], v[34:35], v[18:19] op_sel_hi:[0,1,1]
	v_pk_fma_f32 v[16:17], v[50:51], v[42:43], v[16:17] op_sel_hi:[0,1,1]
	s_waitcnt vmcnt(12)
	v_fmac_f32_e32 v4, v52, v29
	v_pk_fma_f32 v[18:19], v[52:53], v[32:33], v[18:19] op_sel_hi:[0,1,1]
	v_pk_fma_f32 v[16:17], v[52:53], v[40:41], v[16:17] op_sel_hi:[0,1,1]
	v_lshl_add_u64 v[82:83], v[14:15], 0, s[22:23]
	v_add_co_u32_e64 v84, s[0:1], s12, v82
	s_nop 1
	v_addc_co_u32_e64 v85, s[0:1], 0, v83, s[0:1]
	v_add_co_u32_e64 v86, s[0:1], s16, v82
	s_nop 1
	v_addc_co_u32_e64 v87, s[0:1], 0, v83, s[0:1]
	v_add_co_u32_e64 v88, s[0:1], s17, v82
	s_nop 1
	v_addc_co_u32_e64 v89, s[0:1], 0, v83, s[0:1]
	global_load_dword v46, v[82:83], off
	global_load_dword v48, v[84:85], off
	global_load_dword v50, v[86:87], off
	global_load_dword v52, v[88:89], off
	s_add_u32 s24, s22, 0x18000
	s_cmp_lt_u32 s24, 0x300000
	s_cselect_b32 s22, s24, s22
	v_mov_b32_e32 v13, s20
	ds_read_b128 v[26:29], v13
	ds_read_b128 v[30:33], v13 offset:4096
	ds_read_b128 v[34:37], v13 offset:8192
	ds_read_b128 v[38:41], v13 offset:12288
	ds_read_b128 v[42:45], v13 offset:16384
	s_add_u32 s10, s10, 0x18000
	s_addc_u32 s11, s11, 0
	s_waitcnt lgkmcnt(3)
	v_mov_b32_e32 v55, v30
	s_waitcnt lgkmcnt(2)
	v_mov_b32_e32 v54, v34
	s_waitcnt lgkmcnt(1)
	v_mov_b32_e32 v57, v38
	s_waitcnt lgkmcnt(0)
	v_mov_b32_e32 v56, v42
	v_mov_b32_e32 v30, v35
	v_mov_b32_e32 v38, v43
	v_mov_b32_e32 v34, v36
	v_mov_b32_e32 v35, v32
	v_mov_b32_e32 v42, v44
	v_mov_b32_e32 v43, v40
	s_add_i32 s20, s20, 16
	v_mov_b32_e32 v32, v37
	v_mov_b32_e32 v40, v45
	s_waitcnt vmcnt(15)
	v_fmac_f32_e32 v4, v58, v26
	v_pk_fma_f32 v[18:19], v[58:59], v[54:55], v[18:19] op_sel_hi:[0,1,1]
	v_pk_fma_f32 v[16:17], v[58:59], v[56:57], v[16:17] op_sel_hi:[0,1,1]
	s_waitcnt vmcnt(14)
	v_fmac_f32_e32 v4, v60, v27
	v_pk_fma_f32 v[18:19], v[60:61], v[30:31], v[18:19] op_sel_hi:[0,1,1]
	v_pk_fma_f32 v[16:17], v[60:61], v[38:39], v[16:17] op_sel_hi:[0,1,1]
	s_waitcnt vmcnt(13)
	v_fmac_f32_e32 v4, v62, v28
	v_pk_fma_f32 v[18:19], v[62:63], v[34:35], v[18:19] op_sel_hi:[0,1,1]
	v_pk_fma_f32 v[16:17], v[62:63], v[42:43], v[16:17] op_sel_hi:[0,1,1]
	s_waitcnt vmcnt(12)
;     __device__ __forceinline__ const float* in(int i) const { return (const float*)(const __attribute__((address_space(1))) float*)ld(i); }
;     __device__ __forceinline__ unsigned char* ws() const { return (unsigned char*)(__attribute__((address_space(1))) unsigned char*)ld(23); }
; template <int PART>
; __device__ __forceinline__ void prologue(const KPD& kp, unsigned char* lds, int tid, int lane, int wave) {
;     ...
;         for (int k = wave * 128; k < wave * 128 + 128; ++k) { const float wv = w[(size_t)k * 6144];
;             a0 += cs[k] * wv; a1 += cs[1024 + k] * wv; a2 += cs[2048 + k] * wv; a3 += cs[3072 + k] * wv; a4 += cs[4096 + k] * wv; }
;         red[(wave * 5 + 0) * 64 + lane] = a0; red[(wave * 5 + 1) * 64 + lane] = a1; red[(wave * 5 + 2) * 64 + lane] = a2; red[(wave * 5 + 3) * 64 + lane] = a3; red[(wave * 5 + 4) * 64 + lane] = a4;
;         __syncthreads();
;         if (tid < 320) { const int r = tid / 64, c = tid % 64; float s = 0.f;
; #pragma unroll
;             for (int w8 = 0; w8 < 8; ++w8) s += red[(w8 * 5 + r) * 64 + c];
;             ((float*)(ws + WS_MOD))[(size_t)(l * 5 + r) * 6144 + n0 + c] = s + kp.in(I_BADA)[l * 6144 + n0 + c]; }
	v_fmac_f32_e32 v4, v64, v29
	v_pk_fma_f32 v[18:19], v[64:65], v[32:33], v[18:19] op_sel_hi:[0,1,1]
	v_pk_fma_f32 v[16:17], v[64:65], v[40:41], v[16:17] op_sel_hi:[0,1,1]
	v_lshl_add_u64 v[82:83], v[14:15], 0, s[22:23]
	v_add_co_u32_e64 v84, s[0:1], s12, v82
	s_nop 1
	v_addc_co_u32_e64 v85, s[0:1], 0, v83, s[0:1]
	v_add_co_u32_e64 v86, s[0:1], s16, v82
	s_nop 1
	v_addc_co_u32_e64 v87, s[0:1], 0, v83, s[0:1]
	v_add_co_u32_e64 v88, s[0:1], s17, v82
	s_nop 1
	v_addc_co_u32_e64 v89, s[0:1], 0, v83, s[0:1]
	global_load_dword v58, v[82:83], off
	global_load_dword v60, v[84:85], off
	global_load_dword v62, v[86:87], off
	global_load_dword v64, v[88:89], off
	s_add_u32 s24, s22, 0x18000
	s_cmp_lt_u32 s24, 0x300000
	s_cselect_b32 s22, s24, s22
	v_mov_b32_e32 v13, s20
	ds_read_b128 v[26:29], v13
	ds_read_b128 v[30:33], v13 offset:4096
	ds_read_b128 v[34:37], v13 offset:8192
	ds_read_b128 v[38:41], v13 offset:12288
	ds_read_b128 v[42:45], v13 offset:16384
	s_add_u32 s10, s10, 0x18000
	s_addc_u32 s11, s11, 0
	s_waitcnt lgkmcnt(3)
	v_mov_b32_e32 v55, v30
	s_waitcnt lgkmcnt(2)
	v_mov_b32_e32 v54, v34
	s_waitcnt lgkmcnt(1)
	v_mov_b32_e32 v57, v38
	s_waitcnt lgkmcnt(0)
	v_mov_b32_e32 v56, v42
	v_mov_b32_e32 v30, v35
	v_mov_b32_e32 v38, v43
	v_mov_b32_e32 v34, v36
	v_mov_b32_e32 v35, v32
	v_mov_b32_e32 v42, v44
	v_mov_b32_e32 v43, v40
	s_add_i32 s20, s20, 16
	v_mov_b32_e32 v32, v37
	v_mov_b32_e32 v40, v45
	s_waitcnt vmcnt(15)
	v_fmac_f32_e32 v4, v66, v26
	v_pk_fma_f32 v[18:19], v[66:67], v[54:55], v[18:19] op_sel_hi:[0,1,1]
	v_pk_fma_f32 v[16:17], v[66:67], v[56:57], v[16:17] op_sel_hi:[0,1,1]
	s_waitcnt vmcnt(14)
	v_fmac_f32_e32 v4, v68, v27
	v_pk_fma_f32 v[18:19], v[68:69], v[30:31], v[18:19] op_sel_hi:[0,1,1]
	v_pk_fma_f32 v[16:17], v[68:69], v[38:39], v[16:17] op_sel_hi:[0,1,1]
	s_waitcnt vmcnt(13)
	v_fmac_f32_e32 v4, v70, v28
	v_pk_fma_f32 v[18:19], v[70:71], v[34:35], v[18:19] op_sel_hi:[0,1,1]
	v_pk_fma_f32 v[16:17], v[70:71], v[42:43], v[16:17] op_sel_hi:[0,1,1]
	s_waitcnt vmcnt(12)
	v_fmac_f32_e32 v4, v72, v29
	v_pk_fma_f32 v[18:19], v[72:73], v[32:33], v[18:19] op_sel_hi:[0,1,1]
	v_pk_fma_f32 v[16:17], v[72:73], v[40:41], v[16:17] op_sel_hi:[0,1,1]
	v_lshl_add_u64 v[82:83], v[14:15], 0, s[22:23]
	v_add_co_u32_e64 v84, s[0:1], s12, v82
	s_nop 1
	v_addc_co_u32_e64 v85, s[0:1], 0, v83, s[0:1]
	v_add_co_u32_e64 v86, s[0:1], s16, v82
	s_nop 1
	v_addc_co_u32_e64 v87, s[0:1], 0, v83, s[0:1]
	v_add_co_u32_e64 v88, s[0:1], s17, v82
	s_nop 1
	v_addc_co_u32_e64 v89, s[0:1], 0, v83, s[0:1]
	global_load_dword v66, v[82:83], off
	global_load_dword v68, v[84:85], off
	global_load_dword v70, v[86:87], off
	global_load_dword v72, v[88:89], off
	s_add_u32 s24, s22, 0x18000
	s_cmp_lt_u32 s24, 0x300000
	s_cselect_b32 s22, s24, s22
	v_mov_b32_e32 v13, s20
	ds_read_b128 v[26:29], v13
	ds_read_b128 v[30:33], v13 offset:4096
	ds_read_b128 v[34:37], v13 offset:8192
	ds_read_b128 v[38:41], v13 offset:12288
	ds_read_b128 v[42:45], v13 offset:16384
	s_add_u32 s10, s10, 0x18000
	s_addc_u32 s11, s11, 0
	s_waitcnt lgkmcnt(3)
	v_mov_b32_e32 v55, v30
	s_waitcnt lgkmcnt(2)
	v_mov_b32_e32 v54, v34
	s_waitcnt lgkmcnt(1)
	v_mov_b32_e32 v57, v38
	s_waitcnt lgkmcnt(0)
	v_mov_b32_e32 v56, v42
	v_mov_b32_e32 v30, v35
	v_mov_b32_e32 v38, v43
	v_mov_b32_e32 v34, v36
	v_mov_b32_e32 v35, v32
	v_mov_b32_e32 v42, v44
	v_mov_b32_e32 v43, v40
	s_add_i32 s20, s20, 16
	v_mov_b32_e32 v32, v37
	v_mov_b32_e32 v40, v45
	s_waitcnt vmcnt(15)
	v_fmac_f32_e32 v4, v74, v26
	v_pk_fma_f32 v[18:19], v[74:75], v[54:55], v[18:19] op_sel_hi:[0,1,1]
	v_pk_fma_f32 v[16:17], v[74:75], v[56:57], v[16:17] op_sel_hi:[0,1,1]
	s_waitcnt vmcnt(14)
	v_fmac_f32_e32 v4, v76, v27
	v_pk_fma_f32 v[18:19], v[76:77], v[30:31], v[18:19] op_sel_hi:[0,1,1]
	v_pk_fma_f32 v[16:17], v[76:77], v[38:39], v[16:17] op_sel_hi:[0,1,1]
	s_waitcnt vmcnt(13)
	v_fmac_f32_e32 v4, v78, v28
	v_pk_fma_f32 v[18:19], v[78:79], v[34:35], v[18:19] op_sel_hi:[0,1,1]
	v_pk_fma_f32 v[16:17], v[78:79], v[42:43], v[16:17] op_sel_hi:[0,1,1]
	s_waitcnt vmcnt(12)
	v_fmac_f32_e32 v4, v80, v29
	v_pk_fma_f32 v[18:19], v[80:81], v[32:33], v[18:19] op_sel_hi:[0,1,1]
	v_pk_fma_f32 v[16:17], v[80:81], v[40:41], v[16:17] op_sel_hi:[0,1,1]
	s_cmp_eq_u32 s10, 0x300000
	s_cbranch_scc0 .Lpro_loop
	s_waitcnt vmcnt(0)
	ds_write_b32 v1, v4 offset:20480
	ds_write2st64_b32 v3, v19, v18 offset0:81 offset1:82
	ds_write2st64_b32 v3, v17, v16 offset0:83 offset1:84
	s_waitcnt lgkmcnt(0)
	s_barrier
	s_and_saveexec_b64 s[0:1], vcc
	s_cbranch_execz .LBB0_14
	ds_read2st64_b32 v[14:15], v23 offset0:80 offset1:85
	ds_read2st64_b32 v[16:17], v23 offset0:90 offset1:95
	ds_read2st64_b32 v[18:19], v23 offset0:100 offset1:105
	ds_read2st64_b32 v[26:27], v23 offset0:110 offset1:115
	ds_read_b64 v[28:29], v24
	s_waitcnt lgkmcnt(4)
	v_add_f32_e32 v14, 0, v14
	v_add_f32_e32 v14, v14, v15
	s_waitcnt lgkmcnt(3)
	v_add_f32_e32 v14, v14, v16
	v_add_f32_e32 v14, v14, v17
	s_waitcnt lgkmcnt(0)
	v_readfirstlane_b32 s10, v29
	v_readfirstlane_b32 s11, v28
	v_add_f32_e32 v14, v14, v18
	v_mov_b32_e32 v29, s10
	s_mul_i32 s10, s19, 0x1800
	s_add_i32 s10, s10, s8
	v_or_b32_e32 v30, s10, v2
	v_mov_b32_e32 v28, s11
	v_ashrrev_i32_e32 v31, 31, v30
	v_lshl_add_u64 v[28:29], v[30:31], 2, v[28:29]
	global_load_dword v4, v[28:29], off
	v_mad_u64_u32 v[28:29], s[10:11], s19, 5, v[6:7]
	v_mov_b64_e32 v[30:31], s[2:3]
	v_add_f32_e32 v14, v14, v19
	v_mad_i64_i32 v[28:29], s[10:11], v28, s12, v[30:31]
	v_add_f32_e32 v14, v14, v26
	v_mov_b32_e32 v13, v5
	v_lshl_add_u64 v[28:29], s[8:9], 2, v[28:29]
	v_add_f32_e32 v14, v14, v27
	s_waitcnt vmcnt(0)
	v_add_f32_e32 v4, v14, v4
	v_lshl_add_u64 v[14:15], v[28:29], 0, v[12:13]
	global_store_dword v[14:15], v4, off
	s_branch .LBB0_14
